# k13: k12 + pass A retention V-chunk loads issued as one burst with counted waits
# speedup vs baseline: 1.0361x; 1.0094x over previous
; template <bool GLA>
; __device__ __forceinline__ void chunk_tile(const ChunkRaw& raw, const bf16x8 (&wfr)[2], const f32x4 (&bfr)[2], int h, int it, int row, int kq, float lg, float (&carry)[8], float (&bq)[8], float (&qv)[8], float (&kv)[8]) {
;     ...
;     if (GLA) {
;         const u32x4 gsel = (kq == 0) ? raw.g0 : (kq == 1) ? raw.g1 : (u32x4){0u, 0u, 0u, 0u};
;         const bf16x8 gfr = __builtin_bit_cast(bf16x8, gsel);
;         const f32x4 z0 = __builtin_amdgcn_mfma_f32_16x16x32_bf16(wfr[0], gfr, bfr[0], 0, 0, 0), z1 = __builtin_amdgcn_mfma_f32_16x16x32_bf16(wfr[1], gfr, bfr[1], 0, 0, 0);
;         const float z[8] = {z0[0], z0[1], z0[2], z0[3], z1[0], z1[1], z1[2], z1[3]};
; #pragma unroll
;         for (int j = 0; j < 8; ++j) {
;             float la = (fminf(z[j], 0.f) - __logf(1.0f + __expf(-fabsf(z[j])))) * (1.0f / 16.0f);
;             la += __int_as_float(__builtin_amdgcn_update_dpp(0, __float_as_int(la), 0x111, 0xf, 0xf, false));
;             la += __int_as_float(__builtin_amdgcn_update_dpp(0, __float_as_int(la), 0x112, 0xf, 0xf, false));
;             la += __int_as_float(__builtin_amdgcn_update_dpp(0, __float_as_int(la), 0x114, 0xf, 0xf, false));
;             la += __int_as_float(__builtin_amdgcn_update_dpp(0, __float_as_int(la), 0x118, 0xf, 0xf, false));
;             bq[j] = la + carry[j];
;             carry[j] += __int_as_float(__builtin_amdgcn_ds_bpermute((16 * kq + 15) * 4, __float_as_int(la)));
;             qv[j] = q[j] * qs; kv[j] = k[j];
;         }
.LBB0_617:
	s_andn2_saveexec_b64 s[6:7], s[6:7]
	s_or_b64 exec, exec, s[6:7]
	s_waitcnt vmcnt(1)
	v_mfma_f32_16x16x32_bf16 v[4:7], v[16:19], v[0:3], v[4:7]
	s_mov_b32 s6, 0x3f317217
	s_mov_b32 s7, 0x7f800000
	s_waitcnt vmcnt(0) lgkmcnt(14)
	v_add_f32_e32 v11, 0, v75
	v_mfma_f32_16x16x32_bf16 v[0:3], v[20:23], v[0:3], v[12:15]
	v_add_f32_e32 v27, v11, v38
	s_waitcnt lgkmcnt(7)
	v_add_f32_e32 v112, v27, v29
	v_add_f32_e32 v105, 0, v77
	v_max_f32_e32 v12, v4, v4
	v_mul_f32_e64 v4, |v4|, s8
	v_exp_f32_e32 v4, v4
	v_min_f32_e32 v12, 0, v12
	v_add_f32_e32 v82, 0, v82
	v_add_f32_e32 v110, 0, v84
	v_add_f32_e32 v4, 1.0, v4
	v_cmp_gt_f32_e32 vcc, s96, v4
	v_add_f32_e32 v38, v105, v85
	v_add_f32_e32 v84, v82, v89
	v_cndmask_b32_e64 v13, 0, 32, vcc
	v_ldexp_f32 v4, v4, v13
	v_log_f32_e32 v4, v4
	s_waitcnt lgkmcnt(6)
	v_add_f32_e32 v113, v38, v31
	v_add_f32_e32 v31, v84, v98
	s_waitcnt lgkmcnt(3)
	v_add_f32_e32 v116, v84, v99
	v_mul_f32_e32 v13, 0x3f317217, v4
	v_fma_f32 v13, v4, s6, -v13
	v_fmac_f32_e32 v13, 0x3377d1cf, v4
	v_fmac_f32_e32 v13, 0x3f317217, v4
	v_cmp_lt_f32_e64 s[42:43], |v4|, s7
	v_add_f32_e32 v84, v82, v32
	v_add_f32_e32 v109, 0, v41
	v_cndmask_b32_e64 v4, v4, v13, s[42:43]
	v_cndmask_b32_e32 v13, 0, v237, vcc
	v_sub_f32_e32 v4, v4, v13
	v_sub_f32_e32 v4, v12, v4
	v_mul_f32_e32 v12, 0x3d800000, v4
	v_mov_b32_e32 v13, v211
	v_add_f32_e32 v82, v109, v33
	v_add_f32_e32 v107, 0, v79
	v_mov_b32_dpp v13, v12 row_shr:1 row_mask:0xf bank_mask:0xf
	v_fmac_f32_e32 v13, 0x3d800000, v4
	v_add_f32_e32 v79, v107, v86
	v_add_f32_e32 v114, v79, v94
	v_add_f32_dpp v4, v13, v13 row_shr:2 row_mask:0xf bank_mask:0xf bound_ctrl:1
	v_add_f32_e32 v85, v109, v90
	v_add_f32_e32 v86, v110, v91
	v_add_f32_dpp v4, v4, v4 row_shr:4 row_mask:0xf bank_mask:0xf bound_ctrl:1
	v_add_f32_e32 v111, 0, v43
	v_lshlrev_b32_e32 v43, 16, v61
	v_add_f32_dpp v4, v4, v4 row_shr:8 row_mask:0xf bank_mask:0xf bound_ctrl:1
	v_add_f32_e32 v12, v112, v4
	ds_bpermute_b32 v4, v40, v4
	v_and_b32_e32 v41, 0xffff0000, v61
	v_add_f32_e32 v77, v27, v28
	v_add_f32_e32 v61, v38, v30
	v_add_f32_e32 v29, v85, v25
	s_waitcnt lgkmcnt(0)
	v_add_f32_e32 v32, v112, v4
	v_max_f32_e32 v4, v5, v5
	v_mul_f32_e64 v5, |v5|, s8
	v_exp_f32_e32 v5, v5
	v_min_f32_e32 v4, 0, v4
	v_add_f32_e32 v106, v85, v100
	v_add_f32_e32 v27, v86, v26
	v_add_f32_e32 v5, 1.0, v5
	v_cmp_gt_f32_e32 vcc, s96, v5
	v_add_f32_e32 v38, v86, v101
	v_lshlrev_b32_e32 v86, 16, v57
	v_cndmask_b32_e64 v13, 0, 32, vcc
	v_ldexp_f32 v5, v5, v13
	v_log_f32_e32 v5, v5
	v_and_b32_e32 v85, 0xffff0000, v57
	v_add_f32_e32 v57, v110, v34
	v_add_f32_e32 v108, 0, v81
	v_mul_f32_e32 v13, 0x3f317217, v5
	v_fma_f32 v13, v5, s6, -v13
	v_fmac_f32_e32 v13, 0x3377d1cf, v5
	v_fmac_f32_e32 v13, 0x3f317217, v5
	v_cmp_lt_f32_e64 s[42:43], |v5|, s7
	v_add_f32_e32 v81, v108, v88
	v_add_f32_e32 v115, v81, v97
	v_cndmask_b32_e64 v5, v5, v13, s[42:43]
	v_cndmask_b32_e32 v13, 0, v237, vcc
	v_sub_f32_e32 v5, v5, v13
	v_sub_f32_e32 v4, v4, v5
	v_mul_f32_e32 v5, 0x3d800000, v4
	v_mov_b32_e32 v13, v211
	v_lshlrev_b32_e32 v24, 16, v58
	v_and_b32_e32 v10, 0xffff0000, v58
	v_mov_b32_dpp v13, v5 row_shr:1 row_mask:0xf bank_mask:0xf
	v_fmac_f32_e32 v13, 0x3d800000, v4
	v_mul_f32_e64 v5, |v6|, s8
	v_exp_f32_e32 v5, v5
	v_add_f32_dpp v4, v13, v13 row_shr:2 row_mask:0xf bank_mask:0xf bound_ctrl:1
	v_lshlrev_b32_e32 v9, 16, v59
	v_and_b32_e32 v8, 0xffff0000, v59
	v_add_f32_dpp v4, v4, v4 row_shr:4 row_mask:0xf bank_mask:0xf bound_ctrl:1
	v_add_f32_e32 v5, 1.0, v5
	v_cmp_gt_f32_e32 vcc, s96, v5
	v_add_f32_dpp v4, v4, v4 row_shr:8 row_mask:0xf bank_mask:0xf bound_ctrl:1
	v_add_f32_e32 v13, v113, v4
	ds_bpermute_b32 v4, v40, v4
	v_add_f32_e32 v59, v79, v93
	v_add_f32_e32 v58, v81, v95
	v_lshlrev_b32_e32 v90, 16, v56
	v_and_b32_e32 v89, 0xffff0000, v56
	s_waitcnt lgkmcnt(0)
	v_add_f32_e32 v33, v113, v4
	v_max_f32_e32 v4, v6, v6
	v_cndmask_b32_e64 v6, 0, 32, vcc
	v_ldexp_f32 v5, v5, v6
	v_log_f32_e32 v5, v5
	v_min_f32_e32 v4, 0, v4
	v_lshlrev_b32_e32 v81, 16, v54
	v_and_b32_e32 v79, 0xffff0000, v54
	v_mul_f32_e32 v6, 0x3f317217, v5
	v_fma_f32 v6, v5, s6, -v6
	v_fmac_f32_e32 v6, 0x3377d1cf, v5
	v_fmac_f32_e32 v6, 0x3f317217, v5
	v_cmp_lt_f32_e64 s[42:43], |v5|, s7
	v_lshlrev_b32_e32 v56, 16, v55
	v_and_b32_e32 v54, 0xffff0000, v55
	v_cndmask_b32_e64 v5, v5, v6, s[42:43]
	v_cndmask_b32_e32 v6, 0, v237, vcc
	v_sub_f32_e32 v5, v5, v6
	v_sub_f32_e32 v4, v4, v5
	v_mul_f32_e32 v5, 0x3d800000, v4
	v_mov_b32_e32 v6, v211
	v_add_f32_e32 v55, v111, v35
	v_add_f32_e32 v88, v111, v92
	v_mov_b32_dpp v6, v5 row_shr:1 row_mask:0xf bank_mask:0xf
	v_fmac_f32_e32 v6, 0x3d800000, v4
	v_mul_f32_e64 v5, |v7|, s8
	v_exp_f32_e32 v5, v5
	v_add_f32_dpp v4, v6, v6 row_shr:2 row_mask:0xf bank_mask:0xf bound_ctrl:1
	v_add_f32_e32 v92, v11, v36
	v_add_f32_e32 v91, v105, v37
	v_add_f32_dpp v4, v4, v4 row_shr:4 row_mask:0xf bank_mask:0xf bound_ctrl:1
	v_add_f32_e32 v5, 1.0, v5
	v_cmp_gt_f32_e32 vcc, s96, v5
	v_add_f32_dpp v4, v4, v4 row_shr:8 row_mask:0xf bank_mask:0xf bound_ctrl:1
	v_add_f32_e32 v6, v114, v4
	ds_bpermute_b32 v4, v40, v4
	v_add_f32_e32 v104, v88, v103
	v_add_f32_e32 v105, 0, v72
	v_add_f32_e32 v26, v88, v102
	v_add_f32_e32 v88, v107, v39
	s_waitcnt lgkmcnt(0)
; template <bool GLA>
; __device__ __forceinline__ void chunk_tile(const ChunkRaw& raw, const bf16x8 (&wfr)[2], const f32x4 (&bfr)[2], int h, int it, int row, int kq, float lg, float (&carry)[8], float (&bq)[8], float (&qv)[8], float (&kv)[8]) {
;     ...
; #pragma unroll
;         for (int j = 0; j < 8; ++j) {
;             float la = (fminf(z[j], 0.f) - __logf(1.0f + __expf(-fabsf(z[j])))) * (1.0f / 16.0f);
;             la += __int_as_float(__builtin_amdgcn_update_dpp(0, __float_as_int(la), 0x111, 0xf, 0xf, false));
;             la += __int_as_float(__builtin_amdgcn_update_dpp(0, __float_as_int(la), 0x112, 0xf, 0xf, false));
;             la += __int_as_float(__builtin_amdgcn_update_dpp(0, __float_as_int(la), 0x114, 0xf, 0xf, false));
;             la += __int_as_float(__builtin_amdgcn_update_dpp(0, __float_as_int(la), 0x118, 0xf, 0xf, false));
;             bq[j] = la + carry[j];
;             carry[j] += __int_as_float(__builtin_amdgcn_ds_bpermute((16 * kq + 15) * 4, __float_as_int(la)));
;             qv[j] = q[j] * qs; kv[j] = k[j];
;         }
	v_add_f32_e32 v34, v114, v4
	v_max_f32_e32 v4, v7, v7
	v_cndmask_b32_e64 v7, 0, 32, vcc
	v_ldexp_f32 v5, v5, v7
	v_log_f32_e32 v5, v5
	v_min_f32_e32 v4, 0, v4
	v_lshlrev_b32_e32 v103, 16, v48
	v_add_f32_e32 v102, 0, v73
	v_mul_f32_e32 v7, 0x3f317217, v5
	v_fma_f32 v7, v5, s6, -v7
	v_fmac_f32_e32 v7, 0x3377d1cf, v5
	v_fmac_f32_e32 v7, 0x3f317217, v5
	v_cmp_lt_f32_e64 s[42:43], |v5|, s7
	v_and_b32_e32 v101, 0xffff0000, v48
	v_add_f32_e32 v100, 0, v74
	v_cndmask_b32_e64 v5, v5, v7, s[42:43]
	v_cndmask_b32_e32 v7, 0, v237, vcc
	v_sub_f32_e32 v5, v5, v7
	v_sub_f32_e32 v4, v4, v5
	v_mul_f32_e32 v5, 0x3d800000, v4
	v_mov_b32_e32 v7, v211
	v_lshlrev_b32_e32 v98, 16, v49
	v_add_f32_e32 v99, 0, v76
	v_mov_b32_dpp v7, v5 row_shr:1 row_mask:0xf bank_mask:0xf
	v_fmac_f32_e32 v7, 0x3d800000, v4
	v_and_b32_e32 v97, 0xffff0000, v49
	v_add_f32_e32 v76, 0, v78
	v_add_f32_dpp v4, v7, v7 row_shr:2 row_mask:0xf bank_mask:0xf bound_ctrl:1
	v_lshlrev_b32_e32 v95, 16, v46
	v_add_f32_e32 v74, 0, v80
	v_add_f32_dpp v4, v4, v4 row_shr:4 row_mask:0xf bank_mask:0xf bound_ctrl:1
	v_and_b32_e32 v94, 0xffff0000, v46
	v_add_f32_e32 v73, 0, v42
	v_add_f32_dpp v4, v4, v4 row_shr:8 row_mask:0xf bank_mask:0xf bound_ctrl:1
	v_add_f32_e32 v7, v115, v4
	ds_bpermute_b32 v4, v40, v4
	v_lshlrev_b32_e32 v93, 16, v47
	v_add_f32_e32 v72, 0, v83
	v_and_b32_e32 v49, 0xffff0000, v47
	v_add_f32_e32 v87, v108, v87
	s_waitcnt lgkmcnt(0)
	v_add_f32_e32 v35, v115, v4
	v_max_f32_e32 v4, v0, v0
	v_mul_f32_e64 v0, |v0|, s8
	v_exp_f32_e32 v0, v0
	v_min_f32_e32 v4, 0, v4
	v_lshlrev_b32_e32 v75, 16, v60
	v_and_b32_e32 v60, 0xffff0000, v60
	v_add_f32_e32 v0, 1.0, v0
	v_cmp_gt_f32_e32 vcc, s96, v0
	v_lshlrev_b32_e32 v48, 16, v52
	v_lshlrev_b32_e32 v30, 16, v50
	v_cndmask_b32_e64 v5, 0, 32, vcc
	v_ldexp_f32 v0, v0, v5
	v_log_f32_e32 v0, v0
	v_and_b32_e32 v28, 0xffff0000, v50
	v_lshlrev_b32_e32 v25, 16, v51
	v_and_b32_e32 v47, 0xffff0000, v52
	v_mul_f32_e32 v5, 0x3f317217, v0
	v_fma_f32 v5, v0, s6, -v5
	v_fmac_f32_e32 v5, 0x3377d1cf, v0
	v_fmac_f32_e32 v5, 0x3f317217, v0
	v_cmp_lt_f32_e64 s[42:43], |v0|, s7
	v_and_b32_e32 v11, 0xffff0000, v51
	v_lshlrev_b32_e32 v46, 16, v53
	v_cndmask_b32_e64 v0, v0, v5, s[42:43]
	v_cndmask_b32_e32 v5, 0, v237, vcc
	v_sub_f32_e32 v0, v0, v5
	v_sub_f32_e32 v0, v4, v0
	v_mul_f32_e32 v4, 0x3d800000, v0
	v_mov_b32_e32 v5, v211
	v_and_b32_e32 v42, 0xffff0000, v53
	s_nop 0
	v_mov_b32_dpp v5, v4 row_shr:1 row_mask:0xf bank_mask:0xf
	v_fmac_f32_e32 v5, 0x3d800000, v0
	s_nop 1
	v_add_f32_dpp v0, v5, v5 row_shr:2 row_mask:0xf bank_mask:0xf bound_ctrl:1
	s_nop 1
	v_add_f32_dpp v0, v0, v0 row_shr:4 row_mask:0xf bank_mask:0xf bound_ctrl:1
	s_nop 1
	v_add_f32_dpp v4, v0, v0 row_shr:8 row_mask:0xf bank_mask:0xf bound_ctrl:1
	v_add_f32_e32 v0, v116, v4
	ds_bpermute_b32 v4, v40, v4
	s_waitcnt lgkmcnt(0)
	v_add_f32_e32 v36, v116, v4
	v_max_f32_e32 v4, v1, v1
	v_mul_f32_e64 v1, |v1|, s8
	v_exp_f32_e32 v1, v1
	v_min_f32_e32 v4, 0, v4
	v_sub_f32_e32 v0, v36, v0
	v_mul_f32_e32 v0, 0x3fb8aa3b, v0
	v_add_f32_e32 v1, 1.0, v1
	v_cmp_gt_f32_e32 vcc, s96, v1
	v_exp_f32_e32 v0, v0
	s_nop 0
	v_cndmask_b32_e64 v5, 0, 32, vcc
	v_ldexp_f32 v1, v1, v5
	v_log_f32_e32 v1, v1
	v_mul_f32_e32 v0, v0, v30
	v_cvt_pk_bf16_f32 v0, v0, s0
	v_mul_f32_e32 v5, 0x3f317217, v1
	v_fma_f32 v5, v1, s6, -v5
	v_fmac_f32_e32 v5, 0x3377d1cf, v1
	v_fmac_f32_e32 v5, 0x3f317217, v1
	v_cmp_lt_f32_e64 s[42:43], |v1|, s7
	s_nop 1
	v_cndmask_b32_e64 v1, v1, v5, s[42:43]
	v_cndmask_b32_e32 v5, 0, v237, vcc
	v_sub_f32_e32 v1, v1, v5
	v_sub_f32_e32 v1, v4, v1
	v_mul_f32_e32 v4, 0x3d800000, v1
	v_mov_b32_e32 v5, v211
	s_nop 1
	v_mov_b32_dpp v5, v4 row_shr:1 row_mask:0xf bank_mask:0xf
	v_fmac_f32_e32 v5, 0x3d800000, v1
	s_nop 1
	v_add_f32_dpp v1, v5, v5 row_shr:2 row_mask:0xf bank_mask:0xf bound_ctrl:1
	s_nop 1
	v_add_f32_dpp v1, v1, v1 row_shr:4 row_mask:0xf bank_mask:0xf bound_ctrl:1
	s_nop 1
	v_add_f32_dpp v4, v1, v1 row_shr:8 row_mask:0xf bank_mask:0xf bound_ctrl:1
	v_add_f32_e32 v1, v106, v4
	ds_bpermute_b32 v4, v40, v4
	s_waitcnt lgkmcnt(0)
	v_add_f32_e32 v37, v106, v4
	v_max_f32_e32 v4, v2, v2
	v_mul_f32_e64 v2, |v2|, s8
	v_exp_f32_e32 v2, v2
	v_min_f32_e32 v4, 0, v4
	v_add_f32_e32 v2, 1.0, v2
	v_cmp_gt_f32_e32 vcc, s96, v2
	s_nop 1
	v_cndmask_b32_e64 v5, 0, 32, vcc
	v_ldexp_f32 v2, v2, v5
	v_log_f32_e32 v2, v2
	s_nop 0
	v_mul_f32_e32 v5, 0x3f317217, v2
	v_fma_f32 v5, v2, s6, -v5
	v_fmac_f32_e32 v5, 0x3377d1cf, v2
	v_fmac_f32_e32 v5, 0x3f317217, v2
	v_cmp_lt_f32_e64 s[42:43], |v2|, s7
	s_nop 1
	v_cndmask_b32_e64 v2, v2, v5, s[42:43]
	v_cndmask_b32_e32 v5, 0, v237, vcc
	v_sub_f32_e32 v2, v2, v5
	v_sub_f32_e32 v2, v4, v2
	v_mul_f32_e32 v4, 0x3d800000, v2
	v_mov_b32_e32 v5, v211
	s_nop 1
	v_mov_b32_dpp v5, v4 row_shr:1 row_mask:0xf bank_mask:0xf
	v_fmac_f32_e32 v5, 0x3d800000, v2
	s_nop 1
	v_add_f32_dpp v2, v5, v5 row_shr:2 row_mask:0xf bank_mask:0xf bound_ctrl:1
	s_nop 1
	v_add_f32_dpp v2, v2, v2 row_shr:4 row_mask:0xf bank_mask:0xf bound_ctrl:1
	s_nop 1
	v_add_f32_dpp v4, v2, v2 row_shr:8 row_mask:0xf bank_mask:0xf bound_ctrl:1
	v_add_f32_e32 v2, v38, v4
	ds_bpermute_b32 v4, v40, v4
	s_waitcnt lgkmcnt(0)
; __device__ __forceinline__ unsigned cvtpk(float lo, float hi) { f32x2_t v = {lo, hi}; bf16x2_t b = __builtin_convertvector(v, bf16x2_t); return __builtin_bit_cast(unsigned, b); }
; template <bool GLA>
; __device__ __forceinline__ void chunk_tile(const ChunkRaw& raw, const bf16x8 (&wfr)[2], const f32x4 (&bfr)[2], int h, int it, int row, int kq, float lg, float (&carry)[8], float (&bq)[8], float (&qv)[8], float (&kv)[8]) {
;     ...
;         for (int j = 0; j < 8; ++j) {
;             float la = (fminf(z[j], 0.f) - __logf(1.0f + __expf(-fabsf(z[j])))) * (1.0f / 16.0f);
;             la += __int_as_float(__builtin_amdgcn_update_dpp(0, __float_as_int(la), 0x111, 0xf, 0xf, false));
;             la += __int_as_float(__builtin_amdgcn_update_dpp(0, __float_as_int(la), 0x112, 0xf, 0xf, false));
;             la += __int_as_float(__builtin_amdgcn_update_dpp(0, __float_as_int(la), 0x114, 0xf, 0xf, false));
;             la += __int_as_float(__builtin_amdgcn_update_dpp(0, __float_as_int(la), 0x118, 0xf, 0xf, false));
;             bq[j] = la + carry[j];
;             carry[j] += __int_as_float(__builtin_amdgcn_ds_bpermute((16 * kq + 15) * 4, __float_as_int(la)));
;             qv[j] = q[j] * qs; kv[j] = k[j];
;         }
; template <bool GLA>
; __device__ __forceinline__ void chunk_pass_a(const ChunkIn& ci, const float* wgl, int unit, unsigned char* wl, int lane, float* dS, float* dec) {
;     ...
;     unsigned char* kst = wl + 64 * GP;
; #pragma unroll
;     for (int it = 0; it < 4; ++it)
; #pragma unroll
;         for (int j = 0; j < 8; ++j) {
;             const int d = (j < 4) ? (4 * kq + j) : (16 + 4 * kq + (j - 4));
;             const float ks = kk[it][j] * __expf(carry[j] - bq[it][j]);
;             *(bf16_t*)(kst + d * GP + (16 * it + row) * 2) = (bf16_t)(cvtpk(ks, 0.f) & 0xffffu);
;         }
	v_add_f32_e32 v38, v38, v4
	v_max_f32_e32 v4, v3, v3
	v_mul_f32_e64 v3, |v3|, s8
	v_exp_f32_e32 v3, v3
	v_min_f32_e32 v4, 0, v4
	s_mov_b32 s8, 0x1c300000
	v_add_f32_e32 v3, 1.0, v3
	v_cmp_gt_f32_e32 vcc, s96, v3
	s_nop 1
	v_cndmask_b32_e64 v5, 0, 32, vcc
	v_ldexp_f32 v3, v3, v5
	v_log_f32_e32 v3, v3
	s_nop 0
	v_mul_f32_e32 v5, 0x3f317217, v3
	v_fma_f32 v5, v3, s6, -v5
	v_fmac_f32_e32 v5, 0x3377d1cf, v3
	v_fmac_f32_e32 v5, 0x3f317217, v3
	v_cmp_lt_f32_e64 s[42:43], |v3|, s7
	s_movk_i32 s6, 0x240
	v_mad_u32_u24 v15, v69, s6, v70
	v_cndmask_b32_e64 v3, v3, v5, s[42:43]
	v_cndmask_b32_e32 v5, 0, v237, vcc
	v_sub_f32_e32 v3, v3, v5
	v_sub_f32_e32 v3, v4, v3
	v_mul_f32_e32 v4, 0x3d800000, v3
	v_mov_b32_e32 v5, v211
	s_movk_i32 s6, 0x90
	s_nop 0
	v_mov_b32_dpp v5, v4 row_shr:1 row_mask:0xf bank_mask:0xf
	v_fmac_f32_e32 v5, 0x3d800000, v3
	v_or_b32_e32 v4, 1, v71
	v_mad_u32_u24 v16, v4, s6, v70
	v_add_f32_dpp v3, v5, v5 row_shr:2 row_mask:0xf bank_mask:0xf bound_ctrl:1
	s_add_u32 s6, s78, s62
	s_addc_u32 s7, s79, s63
	v_add_f32_dpp v3, v3, v3 row_shr:4 row_mask:0xf bank_mask:0xf bound_ctrl:1
	v_lshlrev_b32_e32 v5, 6, v71
	s_nop 0
	v_add_f32_dpp v3, v3, v3 row_shr:8 row_mask:0xf bank_mask:0xf bound_ctrl:1
	v_add_f32_e32 v14, v104, v3
	ds_bpermute_b32 v3, v40, v3
	s_waitcnt lgkmcnt(0)
	v_add_f32_e32 v39, v104, v3
	v_sub_f32_e32 v3, v32, v105
	v_mul_f32_e32 v3, 0x3fb8aa3b, v3
	v_exp_f32_e32 v3, v3
	s_nop 0
	v_mul_f32_e32 v3, v3, v103
	v_cvt_pk_bf16_f32 v3, v3, s0
	ds_write_b16 v15, v3 offset:9216
	v_sub_f32_e32 v3, v33, v102
	v_mul_f32_e32 v3, 0x3fb8aa3b, v3
	v_exp_f32_e32 v3, v3
	s_nop 0
	v_mul_f32_e32 v3, v3, v101
	v_cvt_pk_bf16_f32 v3, v3, s0
	ds_write_b16 v16, v3 offset:9216
	v_sub_f32_e32 v3, v34, v100
	v_mul_f32_e32 v3, 0x3fb8aa3b, v3
	v_exp_f32_e32 v3, v3
	s_nop 0
	v_mul_f32_e32 v3, v3, v98
	v_cvt_pk_bf16_f32 v3, v3, s0
	ds_write_b16 v16, v3 offset:9360
	v_sub_f32_e32 v3, v35, v99
	v_mul_f32_e32 v3, 0x3fb8aa3b, v3
	v_exp_f32_e32 v3, v3
	s_nop 0
	v_mul_f32_e32 v3, v3, v97
	v_cvt_pk_bf16_f32 v3, v3, s0
	ds_write_b16 v16, v3 offset:9504
	v_sub_f32_e32 v3, v36, v76
	v_mul_f32_e32 v3, 0x3fb8aa3b, v3
	v_exp_f32_e32 v3, v3
	s_nop 0
	v_mul_f32_e32 v3, v3, v95
	v_cvt_pk_bf16_f32 v3, v3, s0
	ds_write_b16 v16, v3 offset:11376
	v_sub_f32_e32 v3, v37, v74
	v_mul_f32_e32 v3, 0x3fb8aa3b, v3
	v_exp_f32_e32 v3, v3
	s_nop 0
	v_mul_f32_e32 v3, v3, v94
	v_cvt_pk_bf16_f32 v3, v3, s0
	ds_write_b16 v16, v3 offset:11520
	v_sub_f32_e32 v3, v38, v73
	v_mul_f32_e32 v3, 0x3fb8aa3b, v3
	v_exp_f32_e32 v3, v3
	s_nop 0
	v_mul_f32_e32 v3, v3, v93
	v_cvt_pk_bf16_f32 v3, v3, s0
	ds_write_b16 v16, v3 offset:11664
	v_sub_f32_e32 v3, v39, v72
	v_mul_f32_e32 v3, 0x3fb8aa3b, v3
	v_exp_f32_e32 v3, v3
	s_nop 0
	v_mul_f32_e32 v3, v3, v49
	v_cvt_pk_bf16_f32 v3, v3, s0
	ds_write_b16 v16, v3 offset:11808
	v_sub_f32_e32 v3, v32, v92
	v_mul_f32_e32 v3, 0x3fb8aa3b, v3
	v_exp_f32_e32 v3, v3
	s_nop 0
	v_mul_f32_e32 v3, v3, v90
	v_cvt_pk_bf16_f32 v3, v3, s0
	ds_write_b16 v15, v3 offset:9248
	v_sub_f32_e32 v3, v33, v91
	v_mul_f32_e32 v3, 0x3fb8aa3b, v3
	v_exp_f32_e32 v3, v3
	s_nop 0
	v_mul_f32_e32 v3, v3, v89
	v_cvt_pk_bf16_f32 v3, v3, s0
	ds_write_b16 v16, v3 offset:9248
	v_sub_f32_e32 v3, v34, v88
	v_mul_f32_e32 v3, 0x3fb8aa3b, v3
	v_exp_f32_e32 v3, v3
	s_nop 0
	v_mul_f32_e32 v3, v3, v86
	v_cvt_pk_bf16_f32 v3, v3, s0
	ds_write_b16 v16, v3 offset:9392
	v_sub_f32_e32 v3, v35, v87
	v_mul_f32_e32 v3, 0x3fb8aa3b, v3
	v_exp_f32_e32 v3, v3
	s_nop 0
	v_mul_f32_e32 v3, v3, v85
	v_cvt_pk_bf16_f32 v3, v3, s0
	ds_write_b16 v16, v3 offset:9536
	v_sub_f32_e32 v3, v36, v84
	v_mul_f32_e32 v3, 0x3fb8aa3b, v3
	v_exp_f32_e32 v3, v3
	s_nop 0
	v_mul_f32_e32 v3, v3, v81
	v_cvt_pk_bf16_f32 v3, v3, s0
	ds_write_b16 v16, v3 offset:11408
	v_sub_f32_e32 v3, v37, v82
	v_mul_f32_e32 v3, 0x3fb8aa3b, v3
	v_exp_f32_e32 v3, v3
	s_nop 0
	v_mul_f32_e32 v3, v3, v79
	v_cvt_pk_bf16_f32 v3, v3, s0
	ds_write_b16 v16, v3 offset:11552
	v_sub_f32_e32 v3, v38, v57
	v_mul_f32_e32 v3, 0x3fb8aa3b, v3
	v_exp_f32_e32 v3, v3
	v_or_b32_e32 v57, 0x80, v5
	v_mul_f32_e32 v3, v3, v56
	v_cvt_pk_bf16_f32 v3, v3, s0
	ds_write_b16 v16, v3 offset:11696
	v_sub_f32_e32 v3, v39, v55
	v_mul_f32_e32 v3, 0x3fb8aa3b, v3
	v_exp_f32_e32 v3, v3
	v_lshlrev_b32_e32 v55, 8, v69
	v_lshlrev_b32_e32 v56, 6, v4
	v_or_b32_e32 v4, v56, v45
	v_mul_f32_e32 v3, v3, v54
	v_cvt_pk_bf16_f32 v3, v3, s0
	ds_write_b16 v16, v3 offset:11840
	v_sub_f32_e32 v3, v32, v77
	v_mul_f32_e32 v3, 0x3fb8aa3b, v3
	v_exp_f32_e32 v3, v3
	s_nop 0
	v_mul_f32_e32 v3, v3, v75
	v_cvt_pk_bf16_f32 v3, v3, s0
	ds_write_b16 v15, v3 offset:9280
	v_sub_f32_e32 v3, v33, v61
	v_mul_f32_e32 v3, 0x3fb8aa3b, v3
	v_exp_f32_e32 v3, v3
	s_nop 0
	v_mul_f32_e32 v3, v3, v60
	v_cvt_pk_bf16_f32 v3, v3, s0
	ds_write_b16 v16, v3 offset:9280
	v_sub_f32_e32 v3, v34, v59
	v_mul_f32_e32 v3, 0x3fb8aa3b, v3
	v_exp_f32_e32 v3, v3
	s_nop 0
	v_mul_f32_e32 v3, v3, v43
	v_cvt_pk_bf16_f32 v3, v3, s0
	ds_write_b16 v16, v3 offset:9424
	v_sub_f32_e32 v3, v35, v58
	v_mul_f32_e32 v3, 0x3fb8aa3b, v3
	v_exp_f32_e32 v3, v3
	v_or_b32_e32 v58, 0xc0, v5
	v_mul_f32_e32 v3, v3, v41
	v_cvt_pk_bf16_f32 v3, v3, s0
	ds_write_b16 v16, v3 offset:9568
	v_sub_f32_e32 v3, v36, v31
	v_mul_f32_e32 v3, 0x3fb8aa3b, v3
	v_exp_f32_e32 v3, v3
	s_nop 0
	v_mul_f32_e32 v3, v3, v24
	v_cvt_pk_bf16_f32 v3, v3, s0
	ds_write_b16 v16, v3 offset:11440
	v_sub_f32_e32 v3, v37, v29
	v_mul_f32_e32 v3, 0x3fb8aa3b, v3
	v_exp_f32_e32 v3, v3
	s_nop 0
	v_mul_f32_e32 v3, v3, v10
	v_cvt_pk_bf16_f32 v3, v3, s0
	ds_write_b16 v16, v3 offset:11584
	v_sub_f32_e32 v3, v38, v27
	v_mul_f32_e32 v3, 0x3fb8aa3b, v3
	v_exp_f32_e32 v3, v3
	s_nop 0
	v_mul_f32_e32 v3, v3, v9
; __device__ __forceinline__ unsigned cvtpk(float lo, float hi) { f32x2_t v = {lo, hi}; bf16x2_t b = __builtin_convertvector(v, bf16x2_t); return __builtin_bit_cast(unsigned, b); }
; __device__ __forceinline__ void chunk_load_vt(const bf16_t* proj, int t0, int vcol, unsigned char* wl, int lane) {
;     const bf16_t* vp = proj + (size_t)(t0 + lane) * DINP + vcol;
; #pragma unroll
;     for (int cidx = 0; cidx < 8; ++cidx) {
;         const u32x4 v = *(const u32x4*)(vp + cidx * 8);
;         const unsigned w4[4] = {v.x, v.y, v.z, v.w};
; #pragma unroll
;         for (int j = 0; j < 4; ++j) {
;             *(bf16_t*)(wl + (cidx * 8 + 2 * j) * GP + lane * 2) = (bf16_t)(w4[j] & 0xffffu);
;             *(bf16_t*)(wl + (cidx * 8 + 2 * j + 1) * GP + lane * 2) = (bf16_t)(w4[j] >> 16);
;         }
;     }
; }
; template <bool GLA>
; __device__ __forceinline__ void chunk_pass_a(const ChunkIn& ci, const float* wgl, int unit, unsigned char* wl, int lane, float* dS, float* dec) {
;     ...
;     for (int it = 0; it < 4; ++it)
; #pragma unroll
;         for (int j = 0; j < 8; ++j) {
;             const int d = (j < 4) ? (4 * kq + j) : (16 + 4 * kq + (j - 4));
;             const float ks = kk[it][j] * __expf(carry[j] - bq[it][j]);
;             *(bf16_t*)(kst + d * GP + (16 * it + row) * 2) = (bf16_t)(cvtpk(ks, 0.f) & 0xffffu);
;         }
	v_cvt_pk_bf16_f32 v3, v3, s0
	ds_write_b16 v16, v3 offset:11728
	v_sub_f32_e32 v3, v39, v26
	v_mul_f32_e32 v3, 0x3fb8aa3b, v3
	v_exp_f32_e32 v3, v3
	s_nop 0
	v_mul_f32_e32 v3, v3, v8
	v_cvt_pk_bf16_f32 v3, v3, s0
	ds_write_b16 v16, v3 offset:11872
	v_sub_f32_e32 v3, v32, v12
	v_mul_f32_e32 v3, 0x3fb8aa3b, v3
	v_exp_f32_e32 v3, v3
	s_nop 0
	v_mul_f32_e32 v3, v3, v48
	v_cvt_pk_bf16_f32 v3, v3, s0
	ds_write_b16 v15, v3 offset:9312
	ds_write_b16 v16, v0 offset:11472
	v_sub_f32_e32 v0, v37, v1
	v_mul_f32_e32 v0, 0x3fb8aa3b, v0
	v_exp_f32_e32 v0, v0
	v_sub_f32_e32 v3, v33, v13
	v_mul_f32_e32 v3, 0x3fb8aa3b, v3
	v_exp_f32_e32 v3, v3
	v_mul_f32_e32 v0, v0, v28
	v_cvt_pk_bf16_f32 v0, v0, s0
	ds_write_b16 v16, v0 offset:11616
	v_sub_f32_e32 v0, v38, v2
	v_mul_f32_e32 v0, 0x3fb8aa3b, v0
	v_exp_f32_e32 v0, v0
	v_mul_f32_e32 v3, v3, v47
	v_cvt_pk_bf16_f32 v3, v3, s0
	ds_write_b16 v16, v3 offset:9312
	v_mul_f32_e32 v0, v0, v25
	v_cvt_pk_bf16_f32 v0, v0, s0
	ds_write_b16 v16, v0 offset:11760
	v_sub_f32_e32 v0, v39, v14
	v_mul_f32_e32 v0, 0x3fb8aa3b, v0
	v_exp_f32_e32 v0, v0
	v_sub_f32_e32 v3, v34, v6
	v_mul_f32_e32 v3, 0x3fb8aa3b, v3
	v_exp_f32_e32 v3, v3
	v_mul_f32_e32 v0, v0, v11
	v_cvt_pk_bf16_f32 v0, v0, s0
	ds_write_b16 v16, v0 offset:11904
	v_or_b32_e32 v0, s3, v68
	v_ashrrev_i32_e32 v1, 31, v0
	v_mul_f32_e32 v3, v3, v46
	v_lshlrev_b64 v[0:1], 12, v[0:1]
	v_cvt_pk_bf16_f32 v3, v3, s0
	v_lshl_add_u64 v[0:1], s[44:45], 0, v[0:1]
	ds_write_b16 v16, v3 offset:9456
	v_sub_f32_e32 v3, v35, v7
	global_load_dwordx4 v[120:123], v[0:1], off offset:1344
	global_load_dwordx4 v[124:127], v[0:1], off offset:1360
	global_load_dwordx4 v[128:131], v[0:1], off offset:1376
	global_load_dwordx4 v[132:135], v[0:1], off offset:1392
	global_load_dwordx4 v[136:139], v[0:1], off offset:1408
	global_load_dwordx4 v[140:143], v[0:1], off offset:1424
	global_load_dwordx4 v[144:147], v[0:1], off offset:1440
	global_load_dwordx4 v[148:151], v[0:1], off offset:1456
	v_mul_f32_e32 v3, 0x3fb8aa3b, v3
	v_exp_f32_e32 v3, v3
	v_readlane_b32 s3, v254, 60
	v_mul_f32_e32 v3, v3, v42
	v_cvt_pk_bf16_f32 v3, v3, s0
	ds_write_b16 v16, v3 offset:9600
	s_waitcnt vmcnt(7)
	ds_write_b16 v67, v120
	ds_write_b16_d16_hi v67, v120 offset:144
	ds_write_b16 v67, v121 offset:288
	ds_write_b16_d16_hi v67, v121 offset:432
	ds_write_b16 v67, v122 offset:576
	ds_write_b16_d16_hi v67, v122 offset:720
	ds_write_b16 v67, v123 offset:864
	ds_write_b16_d16_hi v67, v123 offset:1008
	s_waitcnt vmcnt(6)
	ds_write_b16 v67, v124 offset:1152
	ds_write_b16_d16_hi v67, v124 offset:1296
	ds_write_b16 v67, v125 offset:1440
	ds_write_b16_d16_hi v67, v125 offset:1584
	ds_write_b16 v67, v126 offset:1728
	ds_write_b16_d16_hi v67, v126 offset:1872
	ds_write_b16 v67, v127 offset:2016
	ds_write_b16_d16_hi v67, v127 offset:2160
	s_waitcnt vmcnt(5)
	ds_write_b16 v67, v128 offset:2304
	ds_write_b16_d16_hi v67, v128 offset:2448
	ds_write_b16 v67, v129 offset:2592
	ds_write_b16_d16_hi v67, v129 offset:2736
	ds_write_b16 v67, v130 offset:2880
	ds_write_b16_d16_hi v67, v130 offset:3024
	ds_write_b16 v67, v131 offset:3168
	ds_write_b16_d16_hi v67, v131 offset:3312
	s_waitcnt vmcnt(4)
	ds_write_b16 v67, v132 offset:3456
	ds_write_b16_d16_hi v67, v132 offset:3600
	ds_write_b16 v67, v133 offset:3744
	ds_write_b16_d16_hi v67, v133 offset:3888
	ds_write_b16 v67, v134 offset:4032
	ds_write_b16_d16_hi v67, v134 offset:4176
	ds_write_b16 v67, v135 offset:4320
	ds_write_b16_d16_hi v67, v135 offset:4464
	s_waitcnt vmcnt(3)
	ds_write_b16 v67, v136 offset:4608
	ds_write_b16_d16_hi v67, v136 offset:4752
	ds_write_b16 v67, v137 offset:4896
	ds_write_b16_d16_hi v67, v137 offset:5040
	ds_write_b16 v67, v138 offset:5184
	ds_write_b16_d16_hi v67, v138 offset:5328
	ds_write_b16 v67, v139 offset:5472
	ds_write_b16_d16_hi v67, v139 offset:5616
	s_waitcnt vmcnt(2)
	ds_write_b16 v67, v140 offset:5760
	ds_write_b16_d16_hi v67, v140 offset:5904
	ds_write_b16 v67, v141 offset:6048
	ds_write_b16_d16_hi v67, v141 offset:6192
	ds_write_b16 v67, v142 offset:6336
	ds_write_b16_d16_hi v67, v142 offset:6480
	ds_write_b16 v67, v143 offset:6624
	ds_write_b16_d16_hi v67, v143 offset:6768
	s_waitcnt vmcnt(1)
	ds_write_b16 v67, v144 offset:6912
	ds_write_b16_d16_hi v67, v144 offset:7056
	ds_write_b16 v67, v145 offset:7200
	ds_write_b16_d16_hi v67, v145 offset:7344
	ds_write_b16 v67, v146 offset:7488
	ds_write_b16_d16_hi v67, v146 offset:7632
	ds_write_b16 v67, v147 offset:7776
	ds_write_b16_d16_hi v67, v147 offset:7920
	v_or_b32_e32 v6, v55, v45
	v_lshlrev_b32_e32 v210, 2, v6
	v_lshl_add_u64 v[6:7], s[6:7], 0, v[210:211]
	v_add_co_u32_e32 v46, vcc, s8, v6
	v_lshlrev_b32_e32 v210, 2, v4
	s_waitcnt vmcnt(0)
	ds_write_b16 v67, v148 offset:8064
	ds_write_b16_d16_hi v67, v148 offset:8208
	ds_write_b16 v67, v149 offset:8352
	ds_write_b16_d16_hi v67, v149 offset:8496
	ds_write_b16 v67, v150 offset:8640
	ds_write_b16_d16_hi v67, v150 offset:8784
	ds_write_b16 v67, v151 offset:8928
	ds_write_b16_d16_hi v67, v151 offset:9072
	s_waitcnt vmcnt(0) expcnt(0) lgkmcnt(0)
	v_add3_u32 v54, s3, v66, v44
	v_addc_co_u32_e32 v47, vcc, 0, v7, vcc
	v_lshl_add_u64 v[6:7], s[6:7], 0, v[210:211]
	v_or_b32_e32 v4, v57, v45
	ds_read_b128 v[8:11], v54 offset:9216
	ds_read_b128 v[28:31], v54
	ds_read_b128 v[40:43], v54 offset:9280
	ds_read_b128 v[0:3], v54 offset:64
	v_add_co_u32_e32 v48, vcc, s8, v6
	v_lshlrev_b32_e32 v210, 2, v4
	ds_read_b128 v[20:23], v54 offset:2304
	ds_read_b128 v[24:27], v54 offset:2368
	v_addc_co_u32_e32 v49, vcc, 0, v7, vcc
	v_lshl_add_u64 v[6:7], s[6:7], 0, v[210:211]
	v_or_b32_e32 v4, v58, v45
	v_add_co_u32_e32 v50, vcc, s8, v6
	v_lshlrev_b32_e32 v210, 2, v4
	s_nop 0
	v_addc_co_u32_e32 v51, vcc, 0, v7, vcc
	v_lshl_add_u64 v[4:5], s[6:7], 0, v[210:211]
	v_add_co_u32_e32 v52, vcc, s8, v4
	s_waitcnt lgkmcnt(4)
; template <bool GLA>
; __device__ __forceinline__ void chunk_pass_a(const ChunkIn& ci, const float* wgl, int unit, unsigned char* wl, int lane, float* dS, float* dec) {
;     ...
;     float* out = dS + (size_t)unit * 2048;
; #pragma unroll
;     for (int dt = 0; dt < 2; ++dt)
; #pragma unroll
;         for (int et = 0; et < 4; ++et) {
;             f32x4 acc = {0.f, 0.f, 0.f, 0.f};
; #pragma unroll
;             for (int ks = 0; ks < 2; ++ks) {
;                 const bf16x8 a = *(const bf16x8*)(kst + (16 * dt + row) * GP + (32 * ks + 8 * kq) * 2);
;                 const bf16x8 bb = *(const bf16x8*)(wl + (16 * et + row) * GP + (32 * ks + 8 * kq) * 2);
;                 acc = __builtin_amdgcn_mfma_f32_16x16x32_bf16(a, bb, acc, 0, 0, 0);
;             }
; #pragma unroll
;             for (int r = 0; r < 4; ++r) out[(16 * dt + 4 * kq + r) * 64 + 16 * et + row] = acc[r];
;         }
	v_mfma_f32_16x16x32_bf16 v[12:15], v[8:11], v[28:31], 0
	v_addc_co_u32_e32 v53, vcc, 0, v5, vcc
	s_waitcnt lgkmcnt(1)
	v_mfma_f32_16x16x32_bf16 v[4:7], v[8:11], v[20:23], 0
	v_mfma_f32_16x16x32_bf16 v[12:15], v[40:43], v[0:3], v[12:15]
	s_waitcnt lgkmcnt(0)
	v_mfma_f32_16x16x32_bf16 v[4:7], v[40:43], v[24:27], v[4:7]
	s_nop 5
	global_store_dword v[46:47], v12, off
	global_store_dword v[48:49], v13, off
	global_store_dword v[50:51], v14, off
	global_store_dword v[52:53], v15, off
	global_store_dword v[46:47], v4, off offset:64
	global_store_dword v[48:49], v5, off offset:64
	global_store_dword v[50:51], v6, off offset:64
	global_store_dword v[52:53], v7, off offset:64
	ds_read_b128 v[12:15], v54 offset:4608
	ds_read_b128 v[16:19], v54 offset:4672
	s_waitcnt lgkmcnt(1)
	v_mfma_f32_16x16x32_bf16 v[4:7], v[8:11], v[12:15], 0
	s_waitcnt lgkmcnt(0)
	v_mfma_f32_16x16x32_bf16 v[4:7], v[40:43], v[16:19], v[4:7]
	s_nop 7
	global_store_dword v[46:47], v4, off offset:128
	global_store_dword v[48:49], v5, off offset:128
	global_store_dword v[50:51], v6, off offset:128
	global_store_dword v[52:53], v7, off offset:128
	v_add3_u32 v50, s3, v65, v44
	ds_read_b128 v[4:7], v50
	s_waitcnt lgkmcnt(0)
	v_mfma_f32_16x16x32_bf16 v[46:49], v[8:11], v[4:7], 0
	ds_read_b128 v[8:11], v50 offset:64
	s_waitcnt lgkmcnt(0)
	v_mfma_f32_16x16x32_bf16 v[40:43], v[40:43], v[8:11], v[46:49]
	s_nop 4
	v_or_b32_e32 v46, v55, v62
	v_lshlrev_b32_e32 v210, 2, v46
	v_lshl_add_u64 v[46:47], s[6:7], 0, v[210:211]
	v_add_co_u32_e32 v46, vcc, s8, v46
	s_nop 1
	v_addc_co_u32_e32 v47, vcc, 0, v47, vcc
	global_store_dword v[46:47], v40, off
	v_or_b32_e32 v40, v56, v62
	v_lshlrev_b32_e32 v210, 2, v40
	v_lshl_add_u64 v[46:47], s[6:7], 0, v[210:211]
	v_add_co_u32_e32 v46, vcc, s8, v46
	v_or_b32_e32 v40, v57, v62
	s_nop 0
	v_addc_co_u32_e32 v47, vcc, 0, v47, vcc
	v_lshlrev_b32_e32 v210, 2, v40
	global_store_dword v[46:47], v41, off
	v_lshl_add_u64 v[40:41], s[6:7], 0, v[210:211]
	v_add_co_u32_e32 v40, vcc, s8, v40
	ds_read_b128 v[46:49], v54 offset:11584
	s_nop 0
	v_addc_co_u32_e32 v41, vcc, 0, v41, vcc
	global_store_dword v[40:41], v42, off
	v_or_b32_e32 v40, v58, v62
	v_lshlrev_b32_e32 v210, 2, v40
	v_lshl_add_u64 v[40:41], s[6:7], 0, v[210:211]
	v_add_co_u32_e32 v40, vcc, s8, v40
	s_nop 1
	v_addc_co_u32_e32 v41, vcc, 0, v41, vcc
	global_store_dword v[40:41], v43, off
	ds_read_b128 v[40:43], v54 offset:11520
	s_waitcnt lgkmcnt(0)
	v_mfma_f32_16x16x32_bf16 v[28:31], v[40:43], v[28:31], 0
	v_mfma_f32_16x16x32_bf16 v[0:3], v[46:49], v[0:3], v[28:31]
	s_nop 6
	v_or_b32_e32 v30, 0x400, v55
	v_or_b32_e32 v28, v30, v45
	v_lshlrev_b32_e32 v210, 2, v28
	v_lshl_add_u64 v[28:29], s[6:7], 0, v[210:211]
	v_add_co_u32_e32 v28, vcc, s8, v28
	v_or_b32_e32 v31, 0x440, v55
	s_nop 0
	v_addc_co_u32_e32 v29, vcc, 0, v29, vcc
	global_store_dword v[28:29], v0, off
	v_or_b32_e32 v0, v31, v45
	v_lshlrev_b32_e32 v210, 2, v0
	v_lshl_add_u64 v[28:29], s[6:7], 0, v[210:211]
	v_add_co_u32_e32 v28, vcc, s8, v28
	s_nop 1
	v_addc_co_u32_e32 v29, vcc, 0, v29, vcc
	global_store_dword v[28:29], v1, off
	v_or_b32_e32 v28, 0x480, v55
	v_or_b32_e32 v0, v28, v45
	v_lshlrev_b32_e32 v210, 2, v0
	v_lshl_add_u64 v[0:1], s[6:7], 0, v[210:211]
	v_add_co_u32_e32 v0, vcc, s8, v0
	v_or_b32_e32 v29, 0x4c0, v55
	s_nop 0
	v_addc_co_u32_e32 v1, vcc, 0, v1, vcc
	global_store_dword v[0:1], v2, off
	v_or_b32_e32 v0, v29, v45
	v_lshlrev_b32_e32 v210, 2, v0
	v_lshl_add_u64 v[0:1], s[6:7], 0, v[210:211]
	v_add_co_u32_e32 v0, vcc, s8, v0
	s_nop 1
	v_addc_co_u32_e32 v1, vcc, 0, v1, vcc
	global_store_dword v[0:1], v3, off
	v_mfma_f32_16x16x32_bf16 v[0:3], v[40:43], v[20:23], 0
	v_or_b32_e32 v20, v30, v64
	v_lshlrev_b32_e32 v210, 2, v20
	v_lshl_add_u64 v[20:21], s[6:7], 0, v[210:211]
	v_mfma_f32_16x16x32_bf16 v[0:3], v[46:49], v[24:27], v[0:3]
	v_add_co_u32_e32 v20, vcc, s8, v20
	s_nop 1
	v_addc_co_u32_e32 v21, vcc, 0, v21, vcc
	s_nop 3
	global_store_dword v[20:21], v0, off
	v_or_b32_e32 v0, v31, v64
	v_lshlrev_b32_e32 v210, 2, v0
	v_lshl_add_u64 v[20:21], s[6:7], 0, v[210:211]
	v_add_co_u32_e32 v20, vcc, s8, v20
	v_or_b32_e32 v0, v28, v64
	s_nop 0
	v_addc_co_u32_e32 v21, vcc, 0, v21, vcc
	v_lshlrev_b32_e32 v210, 2, v0
	global_store_dword v[20:21], v1, off
	v_lshl_add_u64 v[0:1], s[6:7], 0, v[210:211]
	v_add_co_u32_e32 v0, vcc, s8, v0
	s_nop 1
	v_addc_co_u32_e32 v1, vcc, 0, v1, vcc
	global_store_dword v[0:1], v2, off
	v_or_b32_e32 v0, v29, v64
	v_lshlrev_b32_e32 v210, 2, v0
	v_lshl_add_u64 v[0:1], s[6:7], 0, v[210:211]
	v_add_co_u32_e32 v0, vcc, s8, v0
	s_nop 1
	v_addc_co_u32_e32 v1, vcc, 0, v1, vcc
	global_store_dword v[0:1], v3, off
	v_mfma_f32_16x16x32_bf16 v[0:3], v[40:43], v[12:15], 0
	v_or_b32_e32 v12, v30, v63
	v_lshlrev_b32_e32 v210, 2, v12
	v_lshl_add_u64 v[12:13], s[6:7], 0, v[210:211]
	v_mfma_f32_16x16x32_bf16 v[0:3], v[46:49], v[16:19], v[0:3]
	v_add_co_u32_e32 v12, vcc, s8, v12
	s_nop 1
	v_addc_co_u32_e32 v13, vcc, 0, v13, vcc
	s_nop 3
	global_store_dword v[12:13], v0, off
	v_or_b32_e32 v0, v31, v63
	v_lshlrev_b32_e32 v210, 2, v0
	v_lshl_add_u64 v[12:13], s[6:7], 0, v[210:211]
	v_add_co_u32_e32 v12, vcc, s8, v12
	v_or_b32_e32 v0, v28, v63
	s_nop 0
	v_addc_co_u32_e32 v13, vcc, 0, v13, vcc
	v_lshlrev_b32_e32 v210, 2, v0
	global_store_dword v[12:13], v1, off
	v_lshl_add_u64 v[0:1], s[6:7], 0, v[210:211]
	v_add_co_u32_e32 v0, vcc, s8, v0
	s_nop 1
	v_addc_co_u32_e32 v1, vcc, 0, v1, vcc
	global_store_dword v[0:1], v2, off
	v_or_b32_e32 v0, v29, v63
	v_lshlrev_b32_e32 v210, 2, v0
	v_lshl_add_u64 v[0:1], s[6:7], 0, v[210:211]
	v_add_co_u32_e32 v0, vcc, s8, v0
	s_nop 1
	v_addc_co_u32_e32 v1, vcc, 0, v1, vcc
	global_store_dword v[0:1], v3, off
	v_mfma_f32_16x16x32_bf16 v[0:3], v[40:43], v[4:7], 0
	v_or_b32_e32 v4, v30, v62
	v_lshlrev_b32_e32 v210, 2, v4
	v_lshl_add_u64 v[4:5], s[6:7], 0, v[210:211]
	v_mfma_f32_16x16x32_bf16 v[0:3], v[46:49], v[8:11], v[0:3]
	v_add_co_u32_e32 v4, vcc, s8, v4
	s_nop 1
	v_addc_co_u32_e32 v5, vcc, 0, v5, vcc
	s_nop 3
	global_store_dword v[4:5], v0, off
	v_or_b32_e32 v0, v31, v62
	v_lshlrev_b32_e32 v210, 2, v0
	v_lshl_add_u64 v[4:5], s[6:7], 0, v[210:211]
	v_add_co_u32_e32 v4, vcc, s8, v4
	v_or_b32_e32 v0, v28, v62
	s_nop 0
	v_addc_co_u32_e32 v5, vcc, 0, v5, vcc
	v_lshlrev_b32_e32 v210, 2, v0
	global_store_dword v[4:5], v1, off
	v_lshl_add_u64 v[0:1], s[6:7], 0, v[210:211]
	v_add_co_u32_e32 v0, vcc, s8, v0
	s_nop 1
	v_addc_co_u32_e32 v1, vcc, 0, v1, vcc
	global_store_dword v[0:1], v2, off
	v_or_b32_e32 v0, v29, v62
	v_lshlrev_b32_e32 v210, 2, v0
	v_lshl_add_u64 v[0:1], s[6:7], 0, v[210:211]
	v_add_co_u32_e32 v0, vcc, 0x1c300000, v0
	s_nop 1
	v_addc_co_u32_e32 v1, vcc, 0, v1, vcc
	v_cmp_eq_u32_e32 vcc, 0, v45
	global_store_dword v[0:1], v3, off
	s_and_saveexec_b64 s[6:7], vcc
	s_cbranch_execz .LBB0_562
; template <bool GLA>
; __device__ __forceinline__ void chunk_pass_a(const ChunkIn& ci, const float* wgl, int unit, unsigned char* wl, int lane, float* dS, float* dec) {
;     ...
;     if (row == 0) {
; #pragma unroll
;         for (int j = 0; j < 8; ++j) { const int d = (j < 4) ? (4 * kq + j) : (16 + 4 * kq + (j - 4)); dec[(size_t)unit * 32 + d] = __expf(carry[j]); }
;     }
	v_mul_f32_e32 v0, 0x3fb8aa3b, v32
	s_add_u32 s8, s78, s50
	v_mul_f32_e32 v1, 0x3fb8aa3b, v33
	v_mul_f32_e32 v2, 0x3fb8aa3b, v34
	v_mul_f32_e32 v3, 0x3fb8aa3b, v35
	v_exp_f32_e32 v0, v0
	v_mov_b32_e32 v45, v211
	s_addc_u32 s9, s79, s51
	v_exp_f32_e32 v1, v1
	v_exp_f32_e32 v2, v2
	v_exp_f32_e32 v3, v3
	v_lshl_add_u64 v[4:5], s[8:9], 0, v[44:45]
	s_mov_b32 s3, 0x1e300000
	v_add_co_u32_e32 v4, vcc, s3, v4
	s_nop 1
	v_addc_co_u32_e32 v5, vcc, 0, v5, vcc
	global_store_dwordx4 v[4:5], v[0:3], off
	s_nop 1
	v_mul_f32_e32 v0, 0x3fb8aa3b, v36
	v_mul_f32_e32 v1, 0x3fb8aa3b, v37
	v_mul_f32_e32 v2, 0x3fb8aa3b, v38
	v_mul_f32_e32 v3, 0x3fb8aa3b, v39
	v_exp_f32_e32 v0, v0
	v_exp_f32_e32 v1, v1
	v_exp_f32_e32 v2, v2
	v_exp_f32_e32 v3, v3
	global_store_dwordx4 v[4:5], v[0:3], off offset:64
	s_branch .LBB0_562
